# P1/P4 tile epilogue stores with sc1 (streamed outputs do not stay in L2)
# baseline (speedup 1.0000x reference)
.LBB0_134:
	v_readlane_b32 s18, v254, 41
	v_lshl_add_u32 v151, s8, 8, v145
	v_lshl_or_b32 v152, s41, 8, v147
	v_readlane_b32 s19, v254, 42
	v_ashrrev_i32_e32 v153, 31, v152
	v_cvt_pk_bf16_f32 v68, v68, v69
	v_mov_b64_e32 v[154:155], s[18:19]
	v_cvt_pk_bf16_f32 v69, v70, v71
	v_cvt_pk_bf16_f32 v70, v64, v65
	v_add_u32_e32 v64, 0x80, v151
	v_mad_i64_i32 v[156:157], s[18:19], v151, s40, v[154:155]
	v_lshlrev_b64 v[152:153], 1, v[152:153]
	v_cvt_pk_bf16_f32 v108, v108, v109
	v_cvt_pk_bf16_f32 v109, v110, v111
	v_cvt_pk_bf16_f32 v110, v104, v105
	v_or_b32_e32 v104, 16, v151
	v_mad_i64_i32 v[64:65], s[18:19], v64, s40, v[154:155]
	v_cvt_pk_bf16_f32 v44, v44, v45
	v_cvt_pk_bf16_f32 v45, v46, v47
	v_cvt_pk_bf16_f32 v46, v40, v41
	v_add_u32_e32 v40, 0x90, v151
	v_lshl_add_u64 v[156:157], v[156:157], 0, v[152:153]
	v_cvt_pk_bf16_f32 v111, v106, v107
	v_mad_i64_i32 v[104:105], s[18:19], v104, s40, v[154:155]
	v_cvt_pk_bf16_f32 v92, v92, v93
	v_cvt_pk_bf16_f32 v93, v94, v95
	v_cvt_pk_bf16_f32 v94, v88, v89
	v_or_b32_e32 v88, 32, v151
	v_lshl_add_u64 v[64:65], v[64:65], 0, v[152:153]
	v_cvt_pk_bf16_f32 v47, v42, v43
	v_mad_i64_i32 v[40:41], s[18:19], v40, s40, v[154:155]
	v_cvt_pk_bf16_f32 v28, v28, v29
	v_cvt_pk_bf16_f32 v29, v30, v31
	v_cvt_pk_bf16_f32 v30, v24, v25
	v_add_u32_e32 v24, 0xa0, v151
	global_store_dwordx4 v[156:157], v[108:111], off offset:256 sc1
	v_cvt_pk_bf16_f32 v95, v90, v91
	v_mad_i64_i32 v[88:89], s[18:19], v88, s40, v[154:155]
	v_lshl_add_u64 v[108:109], v[104:105], 0, v[152:153]
	v_cvt_pk_bf16_f32 v76, v76, v77
	v_cvt_pk_bf16_f32 v77, v78, v79
	v_cvt_pk_bf16_f32 v78, v72, v73
	v_or_b32_e32 v72, 48, v151
	global_store_dwordx4 v[64:65], v[44:47], off offset:256 sc1
	v_cvt_pk_bf16_f32 v31, v26, v27
	v_mad_i64_i32 v[24:25], s[18:19], v24, s40, v[154:155]
	v_lshl_add_u64 v[44:45], v[40:41], 0, v[152:153]
	v_cvt_pk_bf16_f32 v12, v12, v13
	v_cvt_pk_bf16_f32 v13, v14, v15
	v_cvt_pk_bf16_f32 v14, v8, v9
	v_add_u32_e32 v8, 0xb0, v151
	global_store_dwordx4 v[108:109], v[92:95], off offset:256 sc1
	v_cvt_pk_bf16_f32 v79, v74, v75
	v_mad_i64_i32 v[72:73], s[18:19], v72, s40, v[154:155]
	v_lshl_add_u64 v[92:93], v[88:89], 0, v[152:153]
	global_store_dwordx4 v[44:45], v[28:31], off offset:256 sc1
	v_cvt_pk_bf16_f32 v15, v10, v11
	v_mad_i64_i32 v[8:9], s[18:19], v8, s40, v[154:155]
	v_lshl_add_u64 v[28:29], v[24:25], 0, v[152:153]
	v_cvt_pk_bf16_f32 v124, v124, v125
	v_cvt_pk_bf16_f32 v125, v126, v127
	v_cvt_pk_bf16_f32 v126, v120, v121
	v_cvt_pk_bf16_f32 v127, v122, v123
	v_cvt_pk_bf16_f32 v104, v116, v117
	v_cvt_pk_bf16_f32 v105, v118, v119
	v_cvt_pk_bf16_f32 v106, v112, v113
	v_cvt_pk_bf16_f32 v107, v114, v115
	v_cvt_pk_bf16_f32 v88, v100, v101
	v_cvt_pk_bf16_f32 v89, v102, v103
	v_cvt_pk_bf16_f32 v90, v96, v97
	v_cvt_pk_bf16_f32 v91, v98, v99
	global_store_dwordx4 v[92:93], v[76:79], off offset:256 sc1
	v_cvt_pk_bf16_f32 v74, v80, v81
	v_cvt_pk_bf16_f32 v75, v82, v83
	v_lshl_add_u64 v[76:77], v[72:73], 0, v[152:153]
	v_cvt_pk_bf16_f32 v72, v84, v85
	v_cvt_pk_bf16_f32 v73, v86, v87
	v_cvt_pk_bf16_f32 v71, v66, v67
	v_cvt_pk_bf16_f32 v60, v60, v61
	v_cvt_pk_bf16_f32 v61, v62, v63
	v_cvt_pk_bf16_f32 v62, v56, v57
	v_cvt_pk_bf16_f32 v63, v58, v59
	v_cvt_pk_bf16_f32 v40, v52, v53
	v_cvt_pk_bf16_f32 v41, v54, v55
	v_cvt_pk_bf16_f32 v42, v48, v49
	v_cvt_pk_bf16_f32 v43, v50, v51
	v_cvt_pk_bf16_f32 v24, v36, v37
	v_cvt_pk_bf16_f32 v25, v38, v39
	v_cvt_pk_bf16_f32 v26, v32, v33
	v_cvt_pk_bf16_f32 v27, v34, v35
	global_store_dwordx4 v[28:29], v[12:15], off offset:256 sc1
	v_cvt_pk_bf16_f32 v10, v16, v17
	v_cvt_pk_bf16_f32 v11, v18, v19
	v_lshl_add_u64 v[12:13], v[8:9], 0, v[152:153]
	v_cvt_pk_bf16_f32 v8, v20, v21
	v_cvt_pk_bf16_f32 v9, v22, v23
	v_cvt_pk_bf16_f32 v4, v4, v5
	v_cvt_pk_bf16_f32 v5, v6, v7
	v_cvt_pk_bf16_f32 v6, v0, v1
	v_cvt_pk_bf16_f32 v7, v2, v3
	s_andn2_b64 vcc, exec, s[0:1]
	s_mov_b64 s[0:1], -1
	global_store_dwordx4 v[156:157], v[124:127], off sc1
	global_store_dwordx4 v[108:109], v[104:107], off sc1
	global_store_dwordx4 v[92:93], v[88:91], off sc1
	global_store_dwordx4 v[76:77], v[72:75], off sc1
	global_store_dwordx4 v[76:77], v[68:71], off offset:256 sc1
	global_store_dwordx4 v[64:65], v[60:63], off sc1
	global_store_dwordx4 v[44:45], v[40:43], off sc1
	global_store_dwordx4 v[28:29], v[24:27], off sc1
	global_store_dwordx4 v[12:13], v[8:11], off sc1
	global_store_dwordx4 v[12:13], v[4:7], off offset:256 sc1
	s_cbranch_vccnz .LBB0_127
	s_andn2_b64 vcc, exec, s[2:3]
	s_cbranch_vccnz .LBB0_126
	s_barrier
	s_branch .LBB0_126

.LBB0_503:
	v_max_f32_e32 v120, v120, v120
	v_max_f32_e32 v121, v121, v121
	v_max_f32_e32 v120, 0, v120
	v_max_f32_e32 v121, 0, v121
	s_waitcnt vmcnt(0)
	v_mul_f32_e32 v158, v175, v175
	v_pk_mul_f32 v[120:121], v[120:121], v[120:121]
	v_max_f32_e32 v124, v124, v124
	v_pk_mul_f32 v[160:161], v[158:159], v[120:121] op_sel_hi:[0,1]
	v_max_f32_e32 v121, v122, v122
	v_max_f32_e32 v120, v126, v126
	v_max_f32_e32 v122, 0, v121
	v_max_f32_e32 v121, v127, v127
	v_max_f32_e32 v125, v125, v125
	v_max_f32_e32 v120, 0, v120
	v_max_f32_e32 v121, 0, v121
	v_max_f32_e32 v123, v123, v123
	v_lshl_or_b32 v154, s48, 8, v166
	v_readlane_b32 s26, v254, 39
	v_max_f32_e32 v124, 0, v124
	v_max_f32_e32 v125, 0, v125
	v_max_f32_e32 v123, 0, v123
	v_pk_mul_f32 v[120:121], v[120:121], v[120:121]
	v_ashrrev_i32_e32 v155, 31, v154
	v_lshlrev_b64 v[156:157], 13, v[152:153]
	v_readlane_b32 s27, v254, 40
	v_pk_mul_f32 v[124:125], v[124:125], v[124:125]
	v_pk_mul_f32 v[126:127], v[158:159], v[120:121] op_sel_hi:[0,1]
	v_pk_mul_f32 v[120:121], v[122:123], v[122:123]
	v_max_f32_e32 v112, v112, v112
	v_max_f32_e32 v113, v113, v113
	v_lshl_add_u64 v[156:157], s[26:27], 0, v[156:157]
	v_lshlrev_b64 v[154:155], 1, v[154:155]
	v_pk_mul_f32 v[124:125], v[158:159], v[124:125] op_sel_hi:[0,1]
	v_pk_mul_f32 v[162:163], v[158:159], v[120:121] op_sel_hi:[0,1]
	v_max_f32_e32 v112, 0, v112
	v_max_f32_e32 v113, 0, v113
	v_lshl_add_u64 v[156:157], v[156:157], 0, v[154:155]
	v_cvt_pk_bf16_f32 v120, v124, v125
	v_cvt_pk_bf16_f32 v121, v126, v127
	v_cvt_pk_bf16_f32 v122, v160, v161
	v_cvt_pk_bf16_f32 v123, v162, v163
	v_pk_mul_f32 v[112:113], v[112:113], v[112:113]
	global_store_dwordx4 v[156:157], v[120:123], off sc1
	v_max_f32_e32 v116, v116, v116
	v_max_f32_e32 v117, v117, v117
	v_pk_mul_f32 v[120:121], v[158:159], v[112:113] op_sel_hi:[0,1]
	v_max_f32_e32 v113, v114, v114
	v_max_f32_e32 v112, v118, v118
	v_max_f32_e32 v114, 0, v113
	v_max_f32_e32 v113, v119, v119
	v_max_f32_e32 v112, 0, v112
	v_max_f32_e32 v113, 0, v113
	v_max_f32_e32 v115, v115, v115
	v_max_f32_e32 v116, 0, v116
	v_max_f32_e32 v117, 0, v117
	v_max_f32_e32 v115, 0, v115
	v_pk_mul_f32 v[112:113], v[112:113], v[112:113]
	v_pk_mul_f32 v[116:117], v[116:117], v[116:117]
	v_pk_mul_f32 v[118:119], v[158:159], v[112:113] op_sel_hi:[0,1]
	v_pk_mul_f32 v[112:113], v[114:115], v[114:115]
	v_pk_mul_f32 v[116:117], v[158:159], v[116:117] op_sel_hi:[0,1]
	v_pk_mul_f32 v[122:123], v[158:159], v[112:113] op_sel_hi:[0,1]
	v_max_f32_e32 v104, v104, v104
	v_max_f32_e32 v105, v105, v105
	v_cvt_pk_bf16_f32 v112, v116, v117
	v_cvt_pk_bf16_f32 v113, v118, v119
	v_cvt_pk_bf16_f32 v114, v120, v121
	v_cvt_pk_bf16_f32 v115, v122, v123
	v_max_f32_e32 v104, 0, v104
	v_max_f32_e32 v105, 0, v105
	global_store_dwordx4 v[156:157], v[112:115], off offset:256 sc1
	v_pk_mul_f32 v[104:105], v[104:105], v[104:105]
	v_max_f32_e32 v108, v108, v108
	v_mul_f32_e32 v114, v174, v174
	v_pk_mul_f32 v[116:117], v[114:115], v[104:105] op_sel_hi:[0,1]
	v_max_f32_e32 v105, v106, v106
	v_max_f32_e32 v104, v110, v110
	v_max_f32_e32 v106, 0, v105
	v_max_f32_e32 v105, v111, v111
	v_or_b32_e32 v112, 16, v152
	v_max_f32_e32 v109, v109, v109
	v_max_f32_e32 v104, 0, v104
	v_max_f32_e32 v105, 0, v105
	v_max_f32_e32 v107, v107, v107
	v_ashrrev_i32_e32 v113, 31, v112
	v_max_f32_e32 v108, 0, v108
	v_max_f32_e32 v109, 0, v109
	v_max_f32_e32 v107, 0, v107
	v_pk_mul_f32 v[104:105], v[104:105], v[104:105]
	v_lshlrev_b64 v[112:113], 13, v[112:113]
	v_pk_mul_f32 v[108:109], v[108:109], v[108:109]
	v_pk_mul_f32 v[110:111], v[114:115], v[104:105] op_sel_hi:[0,1]
	v_pk_mul_f32 v[104:105], v[106:107], v[106:107]
	v_max_f32_e32 v96, v96, v96
	v_max_f32_e32 v97, v97, v97
	v_lshl_add_u64 v[112:113], s[26:27], 0, v[112:113]
	v_pk_mul_f32 v[108:109], v[114:115], v[108:109] op_sel_hi:[0,1]
	v_pk_mul_f32 v[118:119], v[114:115], v[104:105] op_sel_hi:[0,1]
	v_max_f32_e32 v96, 0, v96
	v_max_f32_e32 v97, 0, v97
	v_lshl_add_u64 v[112:113], v[112:113], 0, v[154:155]
	v_cvt_pk_bf16_f32 v104, v108, v109
	v_cvt_pk_bf16_f32 v105, v110, v111
	v_cvt_pk_bf16_f32 v106, v116, v117
	v_cvt_pk_bf16_f32 v107, v118, v119
	v_pk_mul_f32 v[96:97], v[96:97], v[96:97]
	global_store_dwordx4 v[112:113], v[104:107], off sc1
	v_max_f32_e32 v100, v100, v100
	v_max_f32_e32 v101, v101, v101
	v_pk_mul_f32 v[104:105], v[114:115], v[96:97] op_sel_hi:[0,1]
	v_max_f32_e32 v97, v98, v98
	v_max_f32_e32 v96, v102, v102
	v_max_f32_e32 v98, 0, v97
	v_max_f32_e32 v97, v103, v103
	v_max_f32_e32 v96, 0, v96
	v_max_f32_e32 v97, 0, v97
	v_max_f32_e32 v99, v99, v99
	v_max_f32_e32 v100, 0, v100
	v_max_f32_e32 v101, 0, v101
	v_max_f32_e32 v99, 0, v99
	v_pk_mul_f32 v[96:97], v[96:97], v[96:97]
	v_pk_mul_f32 v[100:101], v[100:101], v[100:101]
	v_pk_mul_f32 v[102:103], v[114:115], v[96:97] op_sel_hi:[0,1]
	v_pk_mul_f32 v[96:97], v[98:99], v[98:99]
	v_pk_mul_f32 v[100:101], v[114:115], v[100:101] op_sel_hi:[0,1]
	v_pk_mul_f32 v[106:107], v[114:115], v[96:97] op_sel_hi:[0,1]
	v_max_f32_e32 v88, v88, v88
	v_max_f32_e32 v89, v89, v89
	v_cvt_pk_bf16_f32 v96, v100, v101
	v_cvt_pk_bf16_f32 v97, v102, v103
	v_cvt_pk_bf16_f32 v98, v104, v105
	v_cvt_pk_bf16_f32 v99, v106, v107
	v_max_f32_e32 v88, 0, v88
	v_max_f32_e32 v89, 0, v89
	global_store_dwordx4 v[112:113], v[96:99], off offset:256 sc1
	v_pk_mul_f32 v[88:89], v[88:89], v[88:89]
	v_max_f32_e32 v92, v92, v92
	v_mul_f32_e32 v98, v173, v173
	v_pk_mul_f32 v[100:101], v[98:99], v[88:89] op_sel_hi:[0,1]
	v_max_f32_e32 v89, v90, v90
	v_max_f32_e32 v88, v94, v94
	v_max_f32_e32 v90, 0, v89
	v_max_f32_e32 v89, v95, v95
	v_or_b32_e32 v96, 32, v152
	v_max_f32_e32 v93, v93, v93
	v_max_f32_e32 v88, 0, v88
	v_max_f32_e32 v89, 0, v89
	v_max_f32_e32 v91, v91, v91
	v_ashrrev_i32_e32 v97, 31, v96
	v_max_f32_e32 v92, 0, v92
	v_max_f32_e32 v93, 0, v93
	v_max_f32_e32 v91, 0, v91
	v_pk_mul_f32 v[88:89], v[88:89], v[88:89]
	v_lshlrev_b64 v[96:97], 13, v[96:97]
	v_pk_mul_f32 v[92:93], v[92:93], v[92:93]
	v_pk_mul_f32 v[94:95], v[98:99], v[88:89] op_sel_hi:[0,1]
	v_pk_mul_f32 v[88:89], v[90:91], v[90:91]
	v_max_f32_e32 v80, v80, v80
	v_max_f32_e32 v81, v81, v81
	v_lshl_add_u64 v[96:97], s[26:27], 0, v[96:97]
	v_pk_mul_f32 v[92:93], v[98:99], v[92:93] op_sel_hi:[0,1]
	v_pk_mul_f32 v[102:103], v[98:99], v[88:89] op_sel_hi:[0,1]
	v_max_f32_e32 v80, 0, v80
	v_max_f32_e32 v81, 0, v81
	v_lshl_add_u64 v[96:97], v[96:97], 0, v[154:155]
	v_cvt_pk_bf16_f32 v88, v92, v93
	v_cvt_pk_bf16_f32 v89, v94, v95
	v_cvt_pk_bf16_f32 v90, v100, v101
	v_cvt_pk_bf16_f32 v91, v102, v103
	v_pk_mul_f32 v[80:81], v[80:81], v[80:81]
	global_store_dwordx4 v[96:97], v[88:91], off sc1
	v_max_f32_e32 v84, v84, v84
	v_max_f32_e32 v85, v85, v85
	v_pk_mul_f32 v[88:89], v[98:99], v[80:81] op_sel_hi:[0,1]
	v_max_f32_e32 v81, v82, v82
	v_max_f32_e32 v80, v86, v86
	v_max_f32_e32 v82, 0, v81
	v_max_f32_e32 v81, v87, v87
	v_max_f32_e32 v80, 0, v80
	v_max_f32_e32 v81, 0, v81
	v_max_f32_e32 v83, v83, v83
	v_max_f32_e32 v84, 0, v84
	v_max_f32_e32 v85, 0, v85
	v_max_f32_e32 v83, 0, v83
	v_pk_mul_f32 v[80:81], v[80:81], v[80:81]
	v_pk_mul_f32 v[84:85], v[84:85], v[84:85]
	v_pk_mul_f32 v[86:87], v[98:99], v[80:81] op_sel_hi:[0,1]
	v_pk_mul_f32 v[80:81], v[82:83], v[82:83]
	v_pk_mul_f32 v[84:85], v[98:99], v[84:85] op_sel_hi:[0,1]
	v_pk_mul_f32 v[90:91], v[98:99], v[80:81] op_sel_hi:[0,1]
	v_max_f32_e32 v72, v72, v72
	v_max_f32_e32 v73, v73, v73
	v_cvt_pk_bf16_f32 v80, v84, v85
	v_cvt_pk_bf16_f32 v81, v86, v87
	v_cvt_pk_bf16_f32 v82, v88, v89
	v_cvt_pk_bf16_f32 v83, v90, v91
	v_max_f32_e32 v72, 0, v72
	v_max_f32_e32 v73, 0, v73
	global_store_dwordx4 v[96:97], v[80:83], off offset:256 sc1
	v_pk_mul_f32 v[72:73], v[72:73], v[72:73]
	v_max_f32_e32 v76, v76, v76
	v_mul_f32_e32 v82, v172, v172
	v_pk_mul_f32 v[84:85], v[82:83], v[72:73] op_sel_hi:[0,1]
	v_max_f32_e32 v73, v74, v74
	v_max_f32_e32 v72, v78, v78
	v_max_f32_e32 v74, 0, v73
	v_max_f32_e32 v73, v79, v79
	v_or_b32_e32 v80, 48, v152
	v_max_f32_e32 v77, v77, v77
	v_max_f32_e32 v72, 0, v72
	v_max_f32_e32 v73, 0, v73
	v_max_f32_e32 v75, v75, v75
	v_ashrrev_i32_e32 v81, 31, v80
	v_max_f32_e32 v76, 0, v76
	v_max_f32_e32 v77, 0, v77
	v_max_f32_e32 v75, 0, v75
	v_pk_mul_f32 v[72:73], v[72:73], v[72:73]
	v_lshlrev_b64 v[80:81], 13, v[80:81]
	v_pk_mul_f32 v[76:77], v[76:77], v[76:77]
	v_pk_mul_f32 v[78:79], v[82:83], v[72:73] op_sel_hi:[0,1]
	v_pk_mul_f32 v[72:73], v[74:75], v[74:75]
	v_max_f32_e32 v64, v64, v64
	v_max_f32_e32 v65, v65, v65
	v_lshl_add_u64 v[80:81], s[26:27], 0, v[80:81]
	v_pk_mul_f32 v[76:77], v[82:83], v[76:77] op_sel_hi:[0,1]
	v_pk_mul_f32 v[86:87], v[82:83], v[72:73] op_sel_hi:[0,1]
	v_max_f32_e32 v64, 0, v64
	v_max_f32_e32 v65, 0, v65
	v_lshl_add_u64 v[80:81], v[80:81], 0, v[154:155]
	v_cvt_pk_bf16_f32 v72, v76, v77
	v_cvt_pk_bf16_f32 v73, v78, v79
	v_cvt_pk_bf16_f32 v74, v84, v85
	v_cvt_pk_bf16_f32 v75, v86, v87
	v_pk_mul_f32 v[64:65], v[64:65], v[64:65]
	global_store_dwordx4 v[80:81], v[72:75], off sc1
	v_max_f32_e32 v68, v68, v68
	v_max_f32_e32 v69, v69, v69
	v_pk_mul_f32 v[72:73], v[82:83], v[64:65] op_sel_hi:[0,1]
	v_max_f32_e32 v65, v66, v66
	v_max_f32_e32 v64, v70, v70
	v_max_f32_e32 v66, 0, v65
	v_max_f32_e32 v65, v71, v71
	v_max_f32_e32 v64, 0, v64
	v_max_f32_e32 v65, 0, v65
	v_max_f32_e32 v67, v67, v67
	v_max_f32_e32 v68, 0, v68
	v_max_f32_e32 v69, 0, v69
	v_max_f32_e32 v67, 0, v67
	v_pk_mul_f32 v[64:65], v[64:65], v[64:65]
	v_pk_mul_f32 v[68:69], v[68:69], v[68:69]
	v_pk_mul_f32 v[70:71], v[82:83], v[64:65] op_sel_hi:[0,1]
	v_pk_mul_f32 v[64:65], v[66:67], v[66:67]
	v_pk_mul_f32 v[68:69], v[82:83], v[68:69] op_sel_hi:[0,1]
	v_pk_mul_f32 v[74:75], v[82:83], v[64:65] op_sel_hi:[0,1]
	v_max_f32_e32 v56, v56, v56
	v_max_f32_e32 v57, v57, v57
	v_cvt_pk_bf16_f32 v64, v68, v69
	v_cvt_pk_bf16_f32 v65, v70, v71
	v_cvt_pk_bf16_f32 v66, v72, v73
	v_cvt_pk_bf16_f32 v67, v74, v75
	v_max_f32_e32 v56, 0, v56
	v_max_f32_e32 v57, 0, v57
	global_store_dwordx4 v[80:81], v[64:67], off offset:256 sc1
	v_pk_mul_f32 v[56:57], v[56:57], v[56:57]
	v_max_f32_e32 v60, v60, v60
	v_mul_f32_e32 v66, v171, v171
	v_pk_mul_f32 v[68:69], v[66:67], v[56:57] op_sel_hi:[0,1]
	v_max_f32_e32 v57, v58, v58
	v_max_f32_e32 v56, v62, v62
	v_max_f32_e32 v58, 0, v57
	v_max_f32_e32 v57, v63, v63
	v_max_f32_e32 v61, v61, v61
	v_max_f32_e32 v56, 0, v56
	v_max_f32_e32 v57, 0, v57
	v_max_f32_e32 v59, v59, v59
	v_max_f32_e32 v60, 0, v60
	v_max_f32_e32 v61, 0, v61
	v_max_f32_e32 v59, 0, v59
	v_pk_mul_f32 v[56:57], v[56:57], v[56:57]
	v_lshlrev_b64 v[64:65], 13, v[150:151]
	v_pk_mul_f32 v[60:61], v[60:61], v[60:61]
	v_pk_mul_f32 v[62:63], v[66:67], v[56:57] op_sel_hi:[0,1]
	v_pk_mul_f32 v[56:57], v[58:59], v[58:59]
	v_max_f32_e32 v48, v48, v48
	v_max_f32_e32 v49, v49, v49
	v_lshl_add_u64 v[64:65], s[26:27], 0, v[64:65]
	v_pk_mul_f32 v[60:61], v[66:67], v[60:61] op_sel_hi:[0,1]
	v_pk_mul_f32 v[70:71], v[66:67], v[56:57] op_sel_hi:[0,1]
	v_max_f32_e32 v48, 0, v48
	v_max_f32_e32 v49, 0, v49
	v_lshl_add_u64 v[64:65], v[64:65], 0, v[154:155]
	v_cvt_pk_bf16_f32 v56, v60, v61
	v_cvt_pk_bf16_f32 v57, v62, v63
	v_cvt_pk_bf16_f32 v58, v68, v69
	v_cvt_pk_bf16_f32 v59, v70, v71
	v_pk_mul_f32 v[48:49], v[48:49], v[48:49]
	global_store_dwordx4 v[64:65], v[56:59], off sc1
	v_max_f32_e32 v52, v52, v52
	v_max_f32_e32 v53, v53, v53
	v_pk_mul_f32 v[56:57], v[66:67], v[48:49] op_sel_hi:[0,1]
	v_max_f32_e32 v49, v50, v50
	v_max_f32_e32 v48, v54, v54
	v_max_f32_e32 v50, 0, v49
	v_max_f32_e32 v49, v55, v55
	v_max_f32_e32 v48, 0, v48
	v_max_f32_e32 v49, 0, v49
	v_max_f32_e32 v51, v51, v51
	v_max_f32_e32 v52, 0, v52
	v_max_f32_e32 v53, 0, v53
	v_max_f32_e32 v51, 0, v51
	v_pk_mul_f32 v[48:49], v[48:49], v[48:49]
	v_pk_mul_f32 v[52:53], v[52:53], v[52:53]
	v_pk_mul_f32 v[54:55], v[66:67], v[48:49] op_sel_hi:[0,1]
	v_pk_mul_f32 v[48:49], v[50:51], v[50:51]
	v_pk_mul_f32 v[52:53], v[66:67], v[52:53] op_sel_hi:[0,1]
	v_pk_mul_f32 v[58:59], v[66:67], v[48:49] op_sel_hi:[0,1]
	v_max_f32_e32 v40, v40, v40
	v_max_f32_e32 v41, v41, v41
	v_cvt_pk_bf16_f32 v48, v52, v53
	v_cvt_pk_bf16_f32 v49, v54, v55
	v_cvt_pk_bf16_f32 v50, v56, v57
	v_cvt_pk_bf16_f32 v51, v58, v59
	v_max_f32_e32 v40, 0, v40
	v_max_f32_e32 v41, 0, v41
	global_store_dwordx4 v[64:65], v[48:51], off offset:256 sc1
	v_pk_mul_f32 v[40:41], v[40:41], v[40:41]
	v_max_f32_e32 v44, v44, v44
	v_mul_f32_e32 v50, v170, v170
	v_pk_mul_f32 v[52:53], v[50:51], v[40:41] op_sel_hi:[0,1]
	v_max_f32_e32 v41, v42, v42
	v_max_f32_e32 v40, v46, v46
	v_max_f32_e32 v42, 0, v41
	v_max_f32_e32 v41, v47, v47
	v_max_f32_e32 v45, v45, v45
	v_max_f32_e32 v40, 0, v40
	v_max_f32_e32 v41, 0, v41
	v_max_f32_e32 v43, v43, v43
	v_max_f32_e32 v44, 0, v44
	v_max_f32_e32 v45, 0, v45
	v_max_f32_e32 v43, 0, v43
	v_pk_mul_f32 v[40:41], v[40:41], v[40:41]
	v_lshlrev_b64 v[48:49], 13, v[148:149]
	v_pk_mul_f32 v[44:45], v[44:45], v[44:45]
	v_pk_mul_f32 v[46:47], v[50:51], v[40:41] op_sel_hi:[0,1]
	v_pk_mul_f32 v[40:41], v[42:43], v[42:43]
	v_max_f32_e32 v32, v32, v32
	v_max_f32_e32 v33, v33, v33
	v_lshl_add_u64 v[48:49], s[26:27], 0, v[48:49]
	v_pk_mul_f32 v[44:45], v[50:51], v[44:45] op_sel_hi:[0,1]
	v_pk_mul_f32 v[54:55], v[50:51], v[40:41] op_sel_hi:[0,1]
	v_max_f32_e32 v32, 0, v32
	v_max_f32_e32 v33, 0, v33
	v_lshl_add_u64 v[48:49], v[48:49], 0, v[154:155]
	v_cvt_pk_bf16_f32 v40, v44, v45
	v_cvt_pk_bf16_f32 v41, v46, v47
	v_cvt_pk_bf16_f32 v42, v52, v53
	v_cvt_pk_bf16_f32 v43, v54, v55
	v_pk_mul_f32 v[32:33], v[32:33], v[32:33]
	global_store_dwordx4 v[48:49], v[40:43], off sc1
	v_max_f32_e32 v36, v36, v36
	v_max_f32_e32 v37, v37, v37
	v_pk_mul_f32 v[40:41], v[50:51], v[32:33] op_sel_hi:[0,1]
	v_max_f32_e32 v33, v34, v34
	v_max_f32_e32 v32, v38, v38
	v_max_f32_e32 v34, 0, v33
	v_max_f32_e32 v33, v39, v39
	v_max_f32_e32 v32, 0, v32
	v_max_f32_e32 v33, 0, v33
	v_max_f32_e32 v35, v35, v35
	v_max_f32_e32 v36, 0, v36
	v_max_f32_e32 v37, 0, v37
	v_max_f32_e32 v35, 0, v35
	v_pk_mul_f32 v[32:33], v[32:33], v[32:33]
	v_pk_mul_f32 v[36:37], v[36:37], v[36:37]
	v_pk_mul_f32 v[38:39], v[50:51], v[32:33] op_sel_hi:[0,1]
	v_pk_mul_f32 v[32:33], v[34:35], v[34:35]
	v_pk_mul_f32 v[36:37], v[50:51], v[36:37] op_sel_hi:[0,1]
	v_pk_mul_f32 v[42:43], v[50:51], v[32:33] op_sel_hi:[0,1]
	v_max_f32_e32 v24, v24, v24
	v_max_f32_e32 v25, v25, v25
	v_cvt_pk_bf16_f32 v32, v36, v37
	v_cvt_pk_bf16_f32 v33, v38, v39
	v_cvt_pk_bf16_f32 v34, v40, v41
	v_cvt_pk_bf16_f32 v35, v42, v43
	v_max_f32_e32 v24, 0, v24
	v_max_f32_e32 v25, 0, v25
	global_store_dwordx4 v[48:49], v[32:35], off offset:256 sc1
	v_pk_mul_f32 v[24:25], v[24:25], v[24:25]
	v_max_f32_e32 v28, v28, v28
	v_mul_f32_e32 v34, v169, v169
	v_pk_mul_f32 v[36:37], v[34:35], v[24:25] op_sel_hi:[0,1]
	v_max_f32_e32 v25, v26, v26
	v_max_f32_e32 v24, v30, v30
	v_max_f32_e32 v26, 0, v25
	v_max_f32_e32 v25, v31, v31
	v_max_f32_e32 v29, v29, v29
	v_max_f32_e32 v24, 0, v24
	v_max_f32_e32 v25, 0, v25
	v_max_f32_e32 v27, v27, v27
	v_max_f32_e32 v28, 0, v28
	v_max_f32_e32 v29, 0, v29
	v_max_f32_e32 v27, 0, v27
	v_pk_mul_f32 v[24:25], v[24:25], v[24:25]
	v_lshlrev_b64 v[32:33], 13, v[146:147]
	v_pk_mul_f32 v[28:29], v[28:29], v[28:29]
	v_pk_mul_f32 v[30:31], v[34:35], v[24:25] op_sel_hi:[0,1]
	v_pk_mul_f32 v[24:25], v[26:27], v[26:27]
	v_max_f32_e32 v16, v16, v16
	v_max_f32_e32 v17, v17, v17
	v_lshl_add_u64 v[32:33], s[26:27], 0, v[32:33]
	v_pk_mul_f32 v[28:29], v[34:35], v[28:29] op_sel_hi:[0,1]
	v_pk_mul_f32 v[38:39], v[34:35], v[24:25] op_sel_hi:[0,1]
	v_max_f32_e32 v16, 0, v16
	v_max_f32_e32 v17, 0, v17
	v_lshl_add_u64 v[32:33], v[32:33], 0, v[154:155]
	v_cvt_pk_bf16_f32 v24, v28, v29
	v_cvt_pk_bf16_f32 v25, v30, v31
	v_cvt_pk_bf16_f32 v26, v36, v37
	v_cvt_pk_bf16_f32 v27, v38, v39
	v_pk_mul_f32 v[16:17], v[16:17], v[16:17]
	global_store_dwordx4 v[32:33], v[24:27], off sc1
	v_max_f32_e32 v20, v20, v20
	v_max_f32_e32 v21, v21, v21
	v_pk_mul_f32 v[24:25], v[34:35], v[16:17] op_sel_hi:[0,1]
	v_max_f32_e32 v17, v18, v18
	v_max_f32_e32 v16, v22, v22
	v_max_f32_e32 v18, 0, v17
	v_max_f32_e32 v17, v23, v23
	v_max_f32_e32 v16, 0, v16
	v_max_f32_e32 v17, 0, v17
	v_max_f32_e32 v19, v19, v19
	v_max_f32_e32 v20, 0, v20
	v_max_f32_e32 v21, 0, v21
	v_max_f32_e32 v19, 0, v19
	v_pk_mul_f32 v[16:17], v[16:17], v[16:17]
	v_pk_mul_f32 v[20:21], v[20:21], v[20:21]
	v_pk_mul_f32 v[22:23], v[34:35], v[16:17] op_sel_hi:[0,1]
	v_pk_mul_f32 v[16:17], v[18:19], v[18:19]
	v_pk_mul_f32 v[20:21], v[34:35], v[20:21] op_sel_hi:[0,1]
	v_pk_mul_f32 v[26:27], v[34:35], v[16:17] op_sel_hi:[0,1]
	v_max_f32_e32 v8, v8, v8
	v_max_f32_e32 v9, v9, v9
	v_cvt_pk_bf16_f32 v16, v20, v21
	v_cvt_pk_bf16_f32 v17, v22, v23
	v_cvt_pk_bf16_f32 v18, v24, v25
	v_cvt_pk_bf16_f32 v19, v26, v27
	v_max_f32_e32 v8, 0, v8
	v_max_f32_e32 v9, 0, v9
	global_store_dwordx4 v[32:33], v[16:19], off offset:256 sc1
	v_pk_mul_f32 v[8:9], v[8:9], v[8:9]
	v_max_f32_e32 v12, v12, v12
	v_mul_f32_e32 v18, v168, v168
	v_pk_mul_f32 v[20:21], v[18:19], v[8:9] op_sel_hi:[0,1]
	v_max_f32_e32 v9, v10, v10
	v_max_f32_e32 v8, v14, v14
	v_max_f32_e32 v10, 0, v9
	v_max_f32_e32 v9, v15, v15
	v_max_f32_e32 v13, v13, v13
	v_max_f32_e32 v8, 0, v8
	v_max_f32_e32 v9, 0, v9
	v_max_f32_e32 v11, v11, v11
	v_max_f32_e32 v12, 0, v12
	v_max_f32_e32 v13, 0, v13
	v_max_f32_e32 v11, 0, v11
	v_pk_mul_f32 v[8:9], v[8:9], v[8:9]
	v_lshlrev_b64 v[16:17], 13, v[144:145]
	v_pk_mul_f32 v[12:13], v[12:13], v[12:13]
	v_pk_mul_f32 v[14:15], v[18:19], v[8:9] op_sel_hi:[0,1]
	v_pk_mul_f32 v[8:9], v[10:11], v[10:11]
	v_max_f32_e32 v0, v0, v0
	v_max_f32_e32 v1, v1, v1
	v_lshl_add_u64 v[16:17], s[26:27], 0, v[16:17]
	v_pk_mul_f32 v[12:13], v[18:19], v[12:13] op_sel_hi:[0,1]
	v_pk_mul_f32 v[22:23], v[18:19], v[8:9] op_sel_hi:[0,1]
	v_max_f32_e32 v0, 0, v0
	v_max_f32_e32 v1, 0, v1
	v_lshl_add_u64 v[16:17], v[16:17], 0, v[154:155]
	v_cvt_pk_bf16_f32 v8, v12, v13
	v_cvt_pk_bf16_f32 v9, v14, v15
	v_cvt_pk_bf16_f32 v10, v20, v21
	v_cvt_pk_bf16_f32 v11, v22, v23
	v_pk_mul_f32 v[0:1], v[0:1], v[0:1]
	global_store_dwordx4 v[16:17], v[8:11], off sc1
	v_max_f32_e32 v4, v4, v4
	v_max_f32_e32 v5, v5, v5
	v_pk_mul_f32 v[8:9], v[18:19], v[0:1] op_sel_hi:[0,1]
	v_max_f32_e32 v1, v2, v2
	v_max_f32_e32 v0, v6, v6
	v_max_f32_e32 v2, 0, v1
	v_max_f32_e32 v1, v7, v7
	v_max_f32_e32 v0, 0, v0
	v_max_f32_e32 v1, 0, v1
	v_max_f32_e32 v3, v3, v3
	v_max_f32_e32 v4, 0, v4
	v_max_f32_e32 v5, 0, v5
	v_max_f32_e32 v3, 0, v3
	v_pk_mul_f32 v[0:1], v[0:1], v[0:1]
	v_pk_mul_f32 v[4:5], v[4:5], v[4:5]
	v_pk_mul_f32 v[6:7], v[18:19], v[0:1] op_sel_hi:[0,1]
	v_pk_mul_f32 v[0:1], v[2:3], v[2:3]
	v_pk_mul_f32 v[4:5], v[18:19], v[4:5] op_sel_hi:[0,1]
	v_pk_mul_f32 v[10:11], v[18:19], v[0:1] op_sel_hi:[0,1]
	v_cvt_pk_bf16_f32 v0, v4, v5
	v_cvt_pk_bf16_f32 v1, v6, v7
	v_cvt_pk_bf16_f32 v2, v8, v9
	v_cvt_pk_bf16_f32 v3, v10, v11
	s_andn2_b64 vcc, exec, s[0:1]
	s_mov_b64 s[0:1], -1
	global_store_dwordx4 v[16:17], v[0:3], off offset:256 sc1
	s_cbranch_vccnz .LBB0_490
	s_andn2_b64 vcc, exec, s[2:3]
	s_cbranch_vccnz .LBB0_489
	s_barrier
	s_branch .LBB0_489
